# attention top-k rank: 63 wave_ror DPP rotations with tie mask instead of 64 ds_bpermute round trips per query
# speedup vs baseline: 1.0039x; 1.0039x over previous
.LBB0_115:
	v_add_u32_e32 v38, s4, v34
	v_and_or_b32 v39, v38, 31, v35
	v_lshl_add_u32 v39, v39, 8, v36
	ds_read2st64_b32 v[40:41], v39 offset1:64
	s_mov_b32 s5, 0
	s_waitcnt lgkmcnt(0)
	v_add_f32_e32 v40, 0, v40
	v_add_f32_e32 v42, v40, v41
	ds_read2st64_b32 v[40:41], v39 offset0:128 offset1:192
	s_waitcnt lgkmcnt(0)
	v_add_f32_e32 v39, v42, v40
	v_add_f32_e32 v39, v39, v41
	v_mov_b32_e32 v40, 0xce6e6b28
	v_cndmask_b32_e64 v39, v39, v40, s[12:13]
	v_mov_b32_e32 v40, 0x4e6e6b28
	v_cndmask_b32_e64 v39, v39, v40, s[10:11]
	v_mov_b32_e32 v41, 0
	v_mov_b32_e32 v40, v37
	v_mov_b32_e32 v42, v39
	s_mov_b64 s[20:21], -1
.LBB0_116:
	s_lshl_b64 s[20:21], s[20:21], 1
	v_mov_b32_dpp v42, v42 wave_ror:1 row_mask:0xf bank_mask:0xf
	v_cmp_eq_f32_e64 s[18:19], v42, v39
	v_cmp_gt_f32_e64 s[16:17], v42, v39
	s_and_b64 s[18:19], s[18:19], s[20:21]
	s_or_b64 s[16:17], s[16:17], s[18:19]
	v_addc_co_u32_e64 v41, s[16:17], 0, v41, s[16:17]
	s_lshl_b64 s[20:21], s[20:21], 1
	v_mov_b32_dpp v42, v42 wave_ror:1 row_mask:0xf bank_mask:0xf
	v_cmp_eq_f32_e64 s[18:19], v42, v39
	v_cmp_gt_f32_e64 s[16:17], v42, v39
	s_and_b64 s[18:19], s[18:19], s[20:21]
	s_or_b64 s[16:17], s[16:17], s[18:19]
	v_addc_co_u32_e64 v41, s[16:17], 0, v41, s[16:17]
	s_lshl_b64 s[20:21], s[20:21], 1
	v_mov_b32_dpp v42, v42 wave_ror:1 row_mask:0xf bank_mask:0xf
	v_cmp_eq_f32_e64 s[18:19], v42, v39
	v_cmp_gt_f32_e64 s[16:17], v42, v39
	s_and_b64 s[18:19], s[18:19], s[20:21]
	s_or_b64 s[16:17], s[16:17], s[18:19]
	v_addc_co_u32_e64 v41, s[16:17], 0, v41, s[16:17]
	s_lshl_b64 s[20:21], s[20:21], 1
	v_mov_b32_dpp v42, v42 wave_ror:1 row_mask:0xf bank_mask:0xf
	v_cmp_eq_f32_e64 s[18:19], v42, v39
	v_cmp_gt_f32_e64 s[16:17], v42, v39
	s_and_b64 s[18:19], s[18:19], s[20:21]
	s_or_b64 s[16:17], s[16:17], s[18:19]
	v_addc_co_u32_e64 v41, s[16:17], 0, v41, s[16:17]
	s_lshl_b64 s[20:21], s[20:21], 1
	v_mov_b32_dpp v42, v42 wave_ror:1 row_mask:0xf bank_mask:0xf
	v_cmp_eq_f32_e64 s[18:19], v42, v39
	v_cmp_gt_f32_e64 s[16:17], v42, v39
	s_and_b64 s[18:19], s[18:19], s[20:21]
	s_or_b64 s[16:17], s[16:17], s[18:19]
	v_addc_co_u32_e64 v41, s[16:17], 0, v41, s[16:17]
	s_lshl_b64 s[20:21], s[20:21], 1
	v_mov_b32_dpp v42, v42 wave_ror:1 row_mask:0xf bank_mask:0xf
	v_cmp_eq_f32_e64 s[18:19], v42, v39
	v_cmp_gt_f32_e64 s[16:17], v42, v39
	s_and_b64 s[18:19], s[18:19], s[20:21]
	s_or_b64 s[16:17], s[16:17], s[18:19]
	v_addc_co_u32_e64 v41, s[16:17], 0, v41, s[16:17]
	s_lshl_b64 s[20:21], s[20:21], 1
	v_mov_b32_dpp v42, v42 wave_ror:1 row_mask:0xf bank_mask:0xf
	v_cmp_eq_f32_e64 s[18:19], v42, v39
	v_cmp_gt_f32_e64 s[16:17], v42, v39
	s_and_b64 s[18:19], s[18:19], s[20:21]
	s_or_b64 s[16:17], s[16:17], s[18:19]
	v_addc_co_u32_e64 v41, s[16:17], 0, v41, s[16:17]
	s_add_i32 s5, s5, 1
	s_cmp_eq_u32 s5, 9
	s_cbranch_scc0 .LBB0_116
	s_branch .Lmy_rank_done
	s_nop 0
	s_nop 0
	s_nop 0
	s_nop 0
	s_nop 0
	s_nop 0
	s_nop 0
	s_nop 0
	s_nop 0
	s_nop 0
	s_nop 0
	s_nop 0
	s_nop 0
	s_nop 0
	s_nop 0
	s_nop 0
	s_nop 0
	s_nop 0
	s_nop 0
	s_nop 0
	s_nop 0
	s_nop 0
	s_nop 0
	s_nop 0
	s_nop 0
	s_nop 0
	s_nop 0
	s_nop 0
	s_nop 0
	s_nop 0
	s_nop 0
	s_nop 0
	s_nop 0
	s_nop 0
	s_nop 0
	s_nop 0
	s_nop 0
	s_nop 0
.Lmy_rank_done:
	v_cmp_gt_u32_e64 s[16:17], 16, v41
	s_and_b64 s[16:17], s[16:17], s[14:15]
	s_nop 0
	v_cndmask_b32_e64 v39, 0, 1, s[16:17]
	v_cmp_ne_u32_e64 s[18:19], 0, v39
	s_and_saveexec_b64 s[16:17], vcc
	s_cbranch_execz .LBB0_114
	v_lshl_add_u32 v38, v38, 3, 0
	v_add_u32_e32 v38, 0x21c00, v38
	v_mov_b64_e32 v[40:41], s[18:19]
	ds_write_b64 v38, v[40:41]
	s_branch .LBB0_114
